# GEMM phases: per-segment s_setprio toggling replaced by one static priority raise for the wave group running one barrier-phase behind
# speedup vs baseline: 1.0073x; 1.0073x over previous
.LBB0_263:
	v_bfe_i32 v2, v6, 27, 1
	v_lshlrev_b32_e32 v0, 4, v6
	v_lshrrev_b32_e32 v2, 22, v2
	v_add_u32_e32 v2, v0, v2
	v_and_b32_e32 v2, 0xfffffc00, v2
	v_sub_u32_e32 v2, v0, v2
	v_ashrrev_i32_e32 v1, 31, v6
	v_lshrrev_b32_e32 v3, 4, v2
	v_lshrrev_b32_e32 v1, 26, v1
	v_bitop3_b32 v3, v3, v2, 32 bitop3:0x6c
	v_ashrrev_i32_e32 v2, 31, v2
	v_add_u32_e32 v1, v6, v1
	v_lshrrev_b32_e32 v2, 26, v2
	v_ashrrev_i32_e32 v1, 6, v1
	v_add_u32_e32 v2, v3, v2
	v_lshlrev_b32_e32 v4, 3, v1
	v_ashrrev_i32_e32 v2, 6, v2
	v_lshlrev_b32_e32 v1, 5, v1
	v_and_b32_e32 v7, 32, v1
	v_mul_i32_i24_e32 v1, 64, v2
	v_sub_u32_e32 v1, v3, v1
	v_and_b32_e32 v4, -16, v4
	v_ashrrev_i16_sdwa v1, v201, sext(v1) dst_sel:DWORD dst_unused:UNUSED_PAD src0_sel:DWORD src1_sel:BYTE_0
	v_add_u32_e32 v4, v2, v4
	v_bfe_i32 v8, v1, 0, 16
	v_add_u32_e32 v1, v7, v8
	v_mul_lo_u32 v9, v4, s4
	v_mul_lo_u32 v2, v4, s0
	v_add_u32_e32 v0, 0x2000, v0
	v_add_lshl_u32 v146, v1, v9, 1
	v_add_lshl_u32 v152, v1, v2, 1
	v_ashrrev_i32_e32 v1, 31, v0
	v_lshrrev_b32_e32 v1, 22, v1
	v_add_u32_e32 v1, v0, v1
	v_ashrrev_i32_e32 v1, 10, v1
	v_mul_i32_i24_e32 v2, 0x400, v1
	v_sub_u32_e32 v0, v0, v2
	v_lshrrev_b32_e32 v2, 4, v0
	v_bitop3_b32 v0, v2, v0, 32 bitop3:0x6c
	v_ashrrev_i32_e32 v3, 31, v0
	v_lshrrev_b32_e32 v3, 26, v3
	v_lshlrev_b32_e32 v2, 3, v1
	v_add_u32_e32 v3, v0, v3
	v_lshlrev_b32_e32 v1, 5, v1
	v_and_b32_e32 v10, 32, v1
	v_and_b32_e32 v1, 0xc0, v3
	v_sub_u32_e32 v0, v0, v1
	v_and_b32_e32 v2, -16, v2
	v_ashrrev_i32_e32 v4, 6, v3
	v_ashrrev_i16_sdwa v0, v201, sext(v0) dst_sel:DWORD dst_unused:UNUSED_PAD src0_sel:DWORD src1_sel:BYTE_0
	v_add_u32_e32 v2, v4, v2
	v_bfe_i32 v11, v0, 0, 16
	s_lshl_b32 s8, s7, 6
	v_add_u32_e32 v0, v10, v11
	s_waitcnt vmcnt(0)
	v_mul_lo_u32 v12, v2, s4
	v_mul_lo_u32 v1, v2, s0
	s_add_i32 s8, s42, s8
	v_add_lshl_u32 v154, v0, v12, 1
	v_add_lshl_u32 v156, v0, v1, 1
	s_ashr_i32 s5, s4, 31
	v_mov_b32_e32 v0, s8
	s_lshl_b64 s[20:21], s[4:5], 8
	s_ashr_i32 s1, s0, 31
	ds_read_b128 v[0:3], v0 offset:5120
	s_lshl_b64 s[24:25], s[4:5], 9
	s_ashr_i32 s10, s44, 31
	s_lshr_b64 s[4:5], s[4:5], 23
	v_writelane_b32 v244, s70, 37
	s_lshl_b64 s[26:27], s[0:1], 9
	s_mul_i32 s10, s24, s10
	s_mul_hi_u32 s11, s24, s44
	s_ashr_i32 s5, s63, 31
	s_ashr_i32 s2, s22, 8
	v_writelane_b32 v244, s22, 38
	s_ashr_i32 s3, s22, 6
	s_lshl_b64 s[22:23], s[0:1], 8
	s_add_i32 s10, s11, s10
	s_mul_i32 s5, s26, s5
	s_mul_hi_u32 s11, s26, s63
	s_lshr_b64 s[0:1], s[0:1], 23
	s_add_i32 s5, s11, s5
	s_mul_i32 s0, s0, s63
	s_lshl_b32 s45, s3, 10
	s_add_i32 s1, s5, s0
	s_mul_i32 s0, s26, s63
	s_waitcnt lgkmcnt(0)
	v_lshl_add_u64 v[130:131], v[2:3], 0, s[0:1]
	s_add_i32 s67, s45, 0
	s_mul_i32 s4, s4, s44
	s_add_i32 m0, s67, 0x12400
	v_readfirstlane_b32 s0, v130
	v_readfirstlane_b32 s1, v131
	v_readfirstlane_b32 s9, v0
	s_add_i32 s10, s10, s4
	s_mul_i32 s4, s24, s44
	v_readfirstlane_b32 s8, v1
	v_lshl_add_u64 v[4:5], v[130:131], 0, s[22:23]
	global_load_lds_dwordx4 v152, s[0:1]
	s_add_i32 m0, s67, 0x14400
	s_add_u32 s4, s9, s4
	s_addc_u32 s5, s8, s10
	s_add_i32 s46, s67, 0x2400
	global_load_lds_dwordx4 v156, s[0:1]
	s_mov_b32 m0, s46
	s_add_i32 s47, s67, 0x4400
	global_load_lds_dwordx4 v146, s[4:5]
	s_mov_b32 m0, s47
	v_readfirstlane_b32 s0, v4
	global_load_lds_dwordx4 v154, s[4:5]
	s_add_i32 m0, s67, 0x16400
	v_readfirstlane_b32 s1, v5
	v_mov_b32_e32 v147, v28
	v_mov_b32_e32 v155, v28
	v_lshl_add_u64 v[2:3], s[4:5], 0, v[146:147]
	v_lshl_add_u64 v[0:1], s[4:5], 0, v[154:155]
	s_nop 0
	global_load_lds_dwordx4 v152, s[0:1]
	s_add_i32 m0, s67, 0x18400
	s_nop 0
	global_load_lds_dwordx4 v156, s[0:1]
	s_add_u32 s0, s4, s20
	s_addc_u32 s1, s5, s21
	s_add_i32 s48, s67, 0x6400
	s_mov_b32 m0, s48
	s_add_i32 s49, s67, 0x8400
	global_load_lds_dwordx4 v146, s[0:1]
	s_mov_b32 m0, s49
	s_cmp_lg_u32 s2, 1
	global_load_lds_dwordx4 v154, s[0:1]
	s_cbranch_scc1 .LBB0_265
	s_setprio 1
	s_barrier

.LBB0_287:
	s_add_i32 s4, s2, 2
	s_add_u32 s5, s0, 0x80
	s_addc_u32 s3, s1, 0
	s_add_i32 s10, 0, 0x12400
	v_add_u32_e32 v144, s10, v151
	ds_read_b128 v[132:135], v144
	ds_read_b128 v[136:139], v144 offset:1024
	ds_read_b128 v[140:143], v144 offset:2048
	ds_read_b128 v[164:167], v144 offset:3072
	s_cmp_eq_u32 s66, s2
	s_cselect_b32 s2, s38, s5
	s_cselect_b64 vcc, -1, 0
	s_cselect_b32 s3, s39, s3
	v_cndmask_b32_e32 v145, v131, v163, vcc
	v_cndmask_b32_e32 v144, v130, v162, vcc
	s_mov_b32 m0, s67
	v_lshl_add_u64 v[248:249], s[0:1], 0, v[160:161]
	ds_read_b128 v[168:171], v176 offset:9216
	ds_read_b128 v[172:175], v176 offset:10240
	ds_read_b128 v[180:183], v176 offset:11264
	ds_read_b128 v[184:187], v176 offset:12288
	ds_read_b128 v[188:191], v176 offset:13312
	ds_read_b128 v[192:195], v176 offset:14336
	ds_read_b128 v[210:213], v176 offset:15360
	ds_read_b128 v[214:217], v176 offset:16384
	s_add_i32 s5, 0, 0x16400
	v_add_u32_e32 v209, s5, v151
	ds_read_b128 v[218:221], v209
	ds_read_b128 v[222:225], v209 offset:1024
	ds_read_b128 v[226:229], v209 offset:2048
	ds_read_b128 v[230:233], v209 offset:3072
	global_load_lds_dwordx4 v[248:249], off
	v_lshl_add_u64 v[250:251], s[0:1], 0, v[158:159]
	s_mov_b32 m0, s73
	s_nop 0
	global_load_lds_dwordx4 v[250:251], off
	s_waitcnt vmcnt(8) lgkmcnt(0)
	s_barrier
	v_mfma_f32_16x16x32_bf16 v[114:117], v[132:135], v[168:171], v[114:117]
	v_mfma_f32_16x16x32_bf16 v[126:129], v[140:143], v[168:171], v[126:129]
	v_mfma_f32_16x16x32_bf16 v[110:113], v[132:135], v[180:183], v[110:113]
	v_mfma_f32_16x16x32_bf16 v[106:109], v[140:143], v[180:183], v[106:109]
	v_mfma_f32_16x16x32_bf16 v[94:97], v[132:135], v[188:191], v[94:97]
	v_mfma_f32_16x16x32_bf16 v[90:93], v[140:143], v[188:191], v[90:93]
	v_mfma_f32_16x16x32_bf16 v[78:81], v[132:135], v[210:213], v[78:81]
	v_mfma_f32_16x16x32_bf16 v[74:77], v[140:143], v[210:213], v[74:77]
	v_mfma_f32_16x16x32_bf16 v[114:117], v[136:139], v[172:175], v[114:117]
	v_mfma_f32_16x16x32_bf16 v[126:129], v[164:167], v[172:175], v[126:129]
	v_mfma_f32_16x16x32_bf16 v[110:113], v[136:139], v[184:187], v[110:113]
	v_mfma_f32_16x16x32_bf16 v[106:109], v[164:167], v[184:187], v[106:109]
	v_mfma_f32_16x16x32_bf16 v[94:97], v[136:139], v[192:195], v[94:97]
	v_mfma_f32_16x16x32_bf16 v[90:93], v[164:167], v[192:195], v[90:93]
	v_mfma_f32_16x16x32_bf16 v[78:81], v[136:139], v[214:217], v[78:81]
	v_mfma_f32_16x16x32_bf16 v[74:77], v[164:167], v[214:217], v[74:77]
	v_mfma_f32_16x16x32_bf16 v[122:125], v[218:221], v[168:171], v[122:125]
	v_mfma_f32_16x16x32_bf16 v[118:121], v[226:229], v[168:171], v[118:121]
	v_mfma_f32_16x16x32_bf16 v[102:105], v[218:221], v[180:183], v[102:105]
	v_mfma_f32_16x16x32_bf16 v[98:101], v[226:229], v[180:183], v[98:101]
	v_mfma_f32_16x16x32_bf16 v[86:89], v[218:221], v[188:191], v[86:89]
	v_mfma_f32_16x16x32_bf16 v[82:85], v[226:229], v[188:191], v[82:85]
	v_mfma_f32_16x16x32_bf16 v[70:73], v[218:221], v[210:213], v[70:73]
	v_mfma_f32_16x16x32_bf16 v[66:69], v[226:229], v[210:213], v[66:69]
	v_mfma_f32_16x16x32_bf16 v[122:125], v[222:225], v[172:175], v[122:125]
	v_mfma_f32_16x16x32_bf16 v[118:121], v[230:233], v[172:175], v[118:121]
	v_mfma_f32_16x16x32_bf16 v[102:105], v[222:225], v[184:187], v[102:105]
	v_mfma_f32_16x16x32_bf16 v[98:101], v[230:233], v[184:187], v[98:101]
	v_mfma_f32_16x16x32_bf16 v[86:89], v[222:225], v[192:195], v[86:89]
	v_mfma_f32_16x16x32_bf16 v[82:85], v[230:233], v[192:195], v[82:85]
	v_mfma_f32_16x16x32_bf16 v[70:73], v[222:225], v[214:217], v[70:73]
	v_mfma_f32_16x16x32_bf16 v[66:69], v[230:233], v[214:217], v[66:69]
	s_barrier
	ds_read_b128 v[168:171], v176 offset:26624
	ds_read_b128 v[172:175], v176 offset:27648
	ds_read_b128 v[180:183], v176 offset:28672
	ds_read_b128 v[184:187], v176 offset:29696
	ds_read_b128 v[188:191], v176 offset:30720
	ds_read_b128 v[192:195], v176 offset:31744
	ds_read_b128 v[210:213], v176 offset:25600
	ds_read_b128 v[214:217], v176 offset:32768
	s_add_i32 s10, s10, s45
	v_lshl_add_u64 v[234:235], v[144:145], 0, v[152:153]
	s_mov_b32 m0, s10
	v_lshl_add_u64 v[236:237], v[144:145], 0, v[156:157]
	global_load_lds_dwordx4 v[234:235], off
	s_add_i32 m0, s10, 0x2000
	v_lshl_add_u64 v[238:239], s[2:3], 0, v[146:147]
	global_load_lds_dwordx4 v[236:237], off
	s_mov_b32 m0, s46
	v_lshl_add_u64 v[240:241], s[2:3], 0, v[154:155]
	global_load_lds_dwordx4 v[238:239], off
	s_mov_b32 m0, s47
	v_lshl_add_u64 v[248:249], v[144:145], 0, s[22:23]
	global_load_lds_dwordx4 v[240:241], off
	s_add_i32 s5, s5, s45
	v_lshl_add_u64 v[144:145], v[248:249], 0, v[152:153]
	s_mov_b32 m0, s5
	v_lshl_add_u64 v[242:243], v[248:249], 0, v[156:157]
	global_load_lds_dwordx4 v[144:145], off
	s_add_i32 m0, s5, 0x2000
	s_nop 0
	global_load_lds_dwordx4 v[242:243], off
	s_waitcnt vmcnt(8) lgkmcnt(0)
	s_barrier
	v_mfma_f32_16x16x32_bf16 v[62:65], v[132:135], v[210:213], v[62:65]
	v_mfma_f32_16x16x32_bf16 v[58:61], v[140:143], v[210:213], v[58:61]
	v_mfma_f32_16x16x32_bf16 v[46:49], v[132:135], v[172:175], v[46:49]
	v_mfma_f32_16x16x32_bf16 v[42:45], v[140:143], v[172:175], v[42:45]
	v_mfma_f32_16x16x32_bf16 v[30:33], v[132:135], v[184:187], v[30:33]
	v_mfma_f32_16x16x32_bf16 v[24:27], v[140:143], v[184:187], v[24:27]
	v_mfma_f32_16x16x32_bf16 v[12:15], v[132:135], v[192:195], v[12:15]
	v_mfma_f32_16x16x32_bf16 v[8:11], v[140:143], v[192:195], v[8:11]
	v_mfma_f32_16x16x32_bf16 v[62:65], v[136:139], v[168:171], v[62:65]
	v_mfma_f32_16x16x32_bf16 v[58:61], v[164:167], v[168:171], v[58:61]
	v_mfma_f32_16x16x32_bf16 v[46:49], v[136:139], v[180:183], v[46:49]
	v_mfma_f32_16x16x32_bf16 v[42:45], v[164:167], v[180:183], v[42:45]
	v_mfma_f32_16x16x32_bf16 v[30:33], v[136:139], v[188:191], v[30:33]
	v_mfma_f32_16x16x32_bf16 v[24:27], v[164:167], v[188:191], v[24:27]
	v_mfma_f32_16x16x32_bf16 v[12:15], v[136:139], v[214:217], v[12:15]
	v_mfma_f32_16x16x32_bf16 v[8:11], v[164:167], v[214:217], v[8:11]
	v_mfma_f32_16x16x32_bf16 v[54:57], v[218:221], v[210:213], v[54:57]
	v_mfma_f32_16x16x32_bf16 v[50:53], v[226:229], v[210:213], v[50:53]
	v_mfma_f32_16x16x32_bf16 v[38:41], v[218:221], v[172:175], v[38:41]
	v_mfma_f32_16x16x32_bf16 v[34:37], v[226:229], v[172:175], v[34:37]
	v_mfma_f32_16x16x32_bf16 v[20:23], v[218:221], v[184:187], v[20:23]
	v_mfma_f32_16x16x32_bf16 v[16:19], v[226:229], v[184:187], v[16:19]
	v_mfma_f32_16x16x32_bf16 v[4:7], v[218:221], v[192:195], v[4:7]
	v_mfma_f32_16x16x32_bf16 v[0:3], v[226:229], v[192:195], v[0:3]
	v_mfma_f32_16x16x32_bf16 v[54:57], v[222:225], v[168:171], v[54:57]
	v_mfma_f32_16x16x32_bf16 v[50:53], v[230:233], v[168:171], v[50:53]
	v_mfma_f32_16x16x32_bf16 v[38:41], v[222:225], v[180:183], v[38:41]
	v_mfma_f32_16x16x32_bf16 v[34:37], v[230:233], v[180:183], v[34:37]
	v_mfma_f32_16x16x32_bf16 v[20:23], v[222:225], v[188:191], v[20:23]
	v_mfma_f32_16x16x32_bf16 v[16:19], v[230:233], v[188:191], v[16:19]
	v_mfma_f32_16x16x32_bf16 v[4:7], v[222:225], v[214:217], v[4:7]
	v_mfma_f32_16x16x32_bf16 v[0:3], v[230:233], v[214:217], v[0:3]
	s_add_i32 s5, 0, 0x1a400
	v_add_u32_e32 v164, s5, v151
	s_barrier
	ds_read_b128 v[132:135], v164
	ds_read_b128 v[136:139], v164 offset:1024
	ds_read_b128 v[140:143], v164 offset:2048
	ds_read_b128 v[164:167], v164 offset:3072
	s_add_u32 s2, s2, s20
	s_addc_u32 s3, s3, s21
	s_mov_b32 m0, s48
	v_lshl_add_u64 v[248:249], s[2:3], 0, v[146:147]
	ds_read_b128 v[168:171], v176 offset:41984
	ds_read_b128 v[172:175], v176 offset:43008
	ds_read_b128 v[180:183], v176 offset:44032
	ds_read_b128 v[184:187], v176 offset:45056
	ds_read_b128 v[188:191], v176 offset:46080
	ds_read_b128 v[192:195], v176 offset:47104
	ds_read_b128 v[210:213], v176 offset:48128
	ds_read_b128 v[214:217], v176 offset:49152
	v_lshl_add_u64 v[250:251], s[2:3], 0, v[154:155]
	s_add_i32 s2, 0, 0x1e400
	v_add_u32_e32 v209, s2, v151
	ds_read_b128 v[218:221], v209
	ds_read_b128 v[222:225], v209 offset:1024
	ds_read_b128 v[226:229], v209 offset:2048
	ds_read_b128 v[230:233], v209 offset:3072
	global_load_lds_dwordx4 v[248:249], off
	s_mov_b32 m0, s49
	s_nop 0
	global_load_lds_dwordx4 v[250:251], off
	s_waitcnt vmcnt(8) lgkmcnt(0)
	s_barrier
	v_mfma_f32_16x16x32_bf16 v[114:117], v[132:135], v[168:171], v[114:117]
	v_mfma_f32_16x16x32_bf16 v[126:129], v[140:143], v[168:171], v[126:129]
	v_mfma_f32_16x16x32_bf16 v[110:113], v[132:135], v[180:183], v[110:113]
	v_mfma_f32_16x16x32_bf16 v[106:109], v[140:143], v[180:183], v[106:109]
	v_mfma_f32_16x16x32_bf16 v[94:97], v[132:135], v[188:191], v[94:97]
	v_mfma_f32_16x16x32_bf16 v[90:93], v[140:143], v[188:191], v[90:93]
	v_mfma_f32_16x16x32_bf16 v[78:81], v[132:135], v[210:213], v[78:81]
	v_mfma_f32_16x16x32_bf16 v[74:77], v[140:143], v[210:213], v[74:77]
	v_mfma_f32_16x16x32_bf16 v[114:117], v[136:139], v[172:175], v[114:117]
	v_mfma_f32_16x16x32_bf16 v[126:129], v[164:167], v[172:175], v[126:129]
	v_mfma_f32_16x16x32_bf16 v[110:113], v[136:139], v[184:187], v[110:113]
	v_mfma_f32_16x16x32_bf16 v[106:109], v[164:167], v[184:187], v[106:109]
	v_mfma_f32_16x16x32_bf16 v[94:97], v[136:139], v[192:195], v[94:97]
	v_mfma_f32_16x16x32_bf16 v[90:93], v[164:167], v[192:195], v[90:93]
	v_mfma_f32_16x16x32_bf16 v[78:81], v[136:139], v[214:217], v[78:81]
	v_mfma_f32_16x16x32_bf16 v[74:77], v[164:167], v[214:217], v[74:77]
	v_mfma_f32_16x16x32_bf16 v[122:125], v[218:221], v[168:171], v[122:125]
	v_mfma_f32_16x16x32_bf16 v[118:121], v[226:229], v[168:171], v[118:121]
	v_mfma_f32_16x16x32_bf16 v[102:105], v[218:221], v[180:183], v[102:105]
	v_mfma_f32_16x16x32_bf16 v[98:101], v[226:229], v[180:183], v[98:101]
	v_mfma_f32_16x16x32_bf16 v[86:89], v[218:221], v[188:191], v[86:89]
	v_mfma_f32_16x16x32_bf16 v[82:85], v[226:229], v[188:191], v[82:85]
	v_mfma_f32_16x16x32_bf16 v[70:73], v[218:221], v[210:213], v[70:73]
	v_mfma_f32_16x16x32_bf16 v[66:69], v[226:229], v[210:213], v[66:69]
	v_mfma_f32_16x16x32_bf16 v[122:125], v[222:225], v[172:175], v[122:125]
	v_mfma_f32_16x16x32_bf16 v[118:121], v[230:233], v[172:175], v[118:121]
	v_mfma_f32_16x16x32_bf16 v[102:105], v[222:225], v[184:187], v[102:105]
	v_mfma_f32_16x16x32_bf16 v[98:101], v[230:233], v[184:187], v[98:101]
	v_mfma_f32_16x16x32_bf16 v[86:89], v[222:225], v[192:195], v[86:89]
	v_mfma_f32_16x16x32_bf16 v[82:85], v[230:233], v[192:195], v[82:85]
	v_mfma_f32_16x16x32_bf16 v[70:73], v[222:225], v[214:217], v[70:73]
	v_mfma_f32_16x16x32_bf16 v[66:69], v[230:233], v[214:217], v[66:69]
	s_barrier
	ds_read_b128 v[168:171], v176 offset:58368
	ds_read_b128 v[172:175], v176 offset:59392
	ds_read_b128 v[180:183], v176 offset:60416
	ds_read_b128 v[184:187], v176 offset:61440
	ds_read_b128 v[188:191], v176 offset:62464
	ds_read_b128 v[192:195], v176 offset:63488
	ds_read_b128 v[210:213], v176 offset:64512
	ds_read_b128 v[214:217], v177 offset:7168
	s_add_i32 s3, s5, s45
	v_lshl_add_u64 v[234:235], v[234:235], 0, s[52:53]
	s_mov_b32 m0, s3
	v_lshl_add_u64 v[236:237], v[236:237], 0, s[52:53]
	global_load_lds_dwordx4 v[234:235], off
	s_add_i32 m0, s3, 0x2000
	v_lshl_add_u64 v[238:239], v[238:239], 0, s[52:53]
	global_load_lds_dwordx4 v[236:237], off
	s_mov_b32 m0, s64
	v_lshl_add_u64 v[240:241], v[240:241], 0, s[52:53]
	global_load_lds_dwordx4 v[238:239], off
	s_mov_b32 m0, s65
	v_lshl_add_u64 v[248:249], v[144:145], 0, s[52:53]
	global_load_lds_dwordx4 v[240:241], off
	s_add_i32 s2, s2, s45
	v_lshl_add_u64 v[250:251], v[242:243], 0, s[52:53]
	s_mov_b32 m0, s2
	s_nop 0
	global_load_lds_dwordx4 v[248:249], off
	s_add_i32 m0, s2, 0x2000
	s_nop 0
	global_load_lds_dwordx4 v[250:251], off
	s_waitcnt vmcnt(8) lgkmcnt(0)
	s_barrier
	v_mfma_f32_16x16x32_bf16 v[62:65], v[132:135], v[168:171], v[62:65]
	v_mfma_f32_16x16x32_bf16 v[58:61], v[140:143], v[168:171], v[58:61]
	v_mfma_f32_16x16x32_bf16 v[46:49], v[132:135], v[180:183], v[46:49]
	v_mfma_f32_16x16x32_bf16 v[42:45], v[140:143], v[180:183], v[42:45]
	v_mfma_f32_16x16x32_bf16 v[30:33], v[132:135], v[188:191], v[30:33]
	v_mfma_f32_16x16x32_bf16 v[24:27], v[140:143], v[188:191], v[24:27]
	v_mfma_f32_16x16x32_bf16 v[12:15], v[132:135], v[210:213], v[12:15]
	v_mfma_f32_16x16x32_bf16 v[8:11], v[140:143], v[210:213], v[8:11]
	v_mfma_f32_16x16x32_bf16 v[62:65], v[136:139], v[172:175], v[62:65]
	v_mfma_f32_16x16x32_bf16 v[58:61], v[164:167], v[172:175], v[58:61]
	v_mfma_f32_16x16x32_bf16 v[46:49], v[136:139], v[184:187], v[46:49]
	v_mfma_f32_16x16x32_bf16 v[42:45], v[164:167], v[184:187], v[42:45]
	v_mfma_f32_16x16x32_bf16 v[30:33], v[136:139], v[192:195], v[30:33]
	v_mfma_f32_16x16x32_bf16 v[24:27], v[164:167], v[192:195], v[24:27]
	v_mfma_f32_16x16x32_bf16 v[12:15], v[136:139], v[214:217], v[12:15]
	v_mfma_f32_16x16x32_bf16 v[8:11], v[164:167], v[214:217], v[8:11]
	v_mfma_f32_16x16x32_bf16 v[54:57], v[218:221], v[168:171], v[54:57]
	v_mfma_f32_16x16x32_bf16 v[50:53], v[226:229], v[168:171], v[50:53]
	v_mfma_f32_16x16x32_bf16 v[38:41], v[218:221], v[180:183], v[38:41]
	v_mfma_f32_16x16x32_bf16 v[34:37], v[226:229], v[180:183], v[34:37]
	v_mfma_f32_16x16x32_bf16 v[20:23], v[218:221], v[188:191], v[20:23]
	v_mfma_f32_16x16x32_bf16 v[16:19], v[226:229], v[188:191], v[16:19]
	v_mfma_f32_16x16x32_bf16 v[4:7], v[218:221], v[210:213], v[4:7]
	v_mfma_f32_16x16x32_bf16 v[0:3], v[226:229], v[210:213], v[0:3]
	v_mfma_f32_16x16x32_bf16 v[54:57], v[222:225], v[172:175], v[54:57]
	v_mfma_f32_16x16x32_bf16 v[50:53], v[230:233], v[172:175], v[50:53]
	v_mfma_f32_16x16x32_bf16 v[38:41], v[222:225], v[184:187], v[38:41]
	v_mfma_f32_16x16x32_bf16 v[34:37], v[230:233], v[184:187], v[34:37]
	v_mfma_f32_16x16x32_bf16 v[20:23], v[222:225], v[192:195], v[20:23]
	v_mfma_f32_16x16x32_bf16 v[16:19], v[230:233], v[192:195], v[16:19]
	v_mfma_f32_16x16x32_bf16 v[4:7], v[222:225], v[214:217], v[4:7]
	v_mfma_f32_16x16x32_bf16 v[0:3], v[230:233], v[214:217], v[0:3]
	s_add_u32 s0, s0, 0x100
	s_addc_u32 s1, s1, 0
	v_lshl_add_u64 v[130:131], v[130:131], 0, s[96:97]
	s_cmp_ge_i32 s4, s62
	s_mov_b32 s2, s4
	s_barrier
	s_cbranch_scc0 .LBB0_287

.LBB0_511:
	s_setprio 0
	s_waitcnt vmcnt(0)
	v_readlane_b32 s0, v244, 38
	s_cmpk_gt_u32 s0, 0xff
	v_readlane_b32 s73, v244, 16
	v_readlane_b32 s70, v244, 37
	s_cbranch_scc1 .LBB0_513
	s_barrier
